# SSD chunk-output tile: gate (z) loads and the per-head scalar load issued after the 4th MFMA of the inter-chunk block into spare registers instead of right before their wait ladder
# baseline (speedup 1.0000x reference)
.LBB0_1844:
	v_add_u32_e32 v10, s2, v1
	ds_read_b128 v[2:5], v10 offset:1024
	ds_read_b128 v[6:9], v10 offset:1536
	v_add_u32_e32 v11, 0x10800, v10
	s_add_i32 s2, s2, 64
	s_cmpk_eq_i32 s2, 0x100
	s_waitcnt lgkmcnt(0)
	v_mfma_f32_32x32x16_bf16 v[72:87], v[2:5], v[6:9], v[72:87]
	v_add_u32_e32 v6, 0x10a00, v10
	ds_read_b128 v[6:9], v6
	s_waitcnt lgkmcnt(0)
	v_mfma_f32_32x32x16_bf16 v[88:103], v[2:5], v[6:9], v[88:103]
	ds_read_b128 v[2:5], v11
	v_add_u32_e32 v11, 0x10820, v10
	s_waitcnt lgkmcnt(0)
	v_mfma_f32_32x32x16_bf16 v[48:63], v[2:5], v[6:9], v[48:63]
	ds_read_b128 v[2:5], v10 offset:1056
	ds_read_b128 v[6:9], v10 offset:1568
	s_waitcnt lgkmcnt(0)
	v_mfma_f32_32x32x16_bf16 v[72:87], v[2:5], v[6:9], v[72:87]
	v_add_u32_e32 v6, 0x10a20, v10
	ds_read_b128 v[6:9], v6
	s_waitcnt lgkmcnt(0)
	v_mfma_f32_32x32x16_bf16 v[88:103], v[2:5], v[6:9], v[88:103]
	ds_read_b128 v[2:5], v11
	s_waitcnt lgkmcnt(0)
	v_mfma_f32_32x32x16_bf16 v[48:63], v[2:5], v[6:9], v[48:63]
	s_cbranch_scc0 .LBB0_1844
	s_lshl_b32 s5, s56, 2
	s_ashr_i32 s53, s52, 31
	s_add_i32 s6, s5, 0
	s_lshl_b64 s[2:3], s[52:53], 17
	s_add_i32 s5, s6, 0x21000
	s_lshl_b64 s[16:17], s[58:59], 14
	s_add_u32 s2, s54, s2
	v_and_b32_e32 v1, 16, v134
	v_or_b32_e32 v185, 32, v186
	v_lshrrev_b32_e32 v2, 2, v134
	v_lshlrev_b32_e32 v188, 2, v186
	s_addc_u32 s3, s55, s3
	v_mov_b32_e32 v214, v112
	v_mov_b32_e32 v215, v137
	v_lshl_add_u64 v[214:215], s[2:3], 0, v[214:215]
	v_lshl_add_u64 v[214:215], s[16:17], 0, v[214:215]
	v_lshlrev_b32_e32 v224, 8, v186
	v_mov_b32_e32 v225, v137
	v_lshl_add_u64 v[214:215], v[214:215], 0, v[224:225]
	v_mov_b32_e32 v224, 0x1797e200
	v_lshl_add_u64 v[204:205], v[214:215], 0, v[224:225]
	v_mov_b32_e32 v224, 0x17980000
	v_lshl_add_u64 v[130:131], v[214:215], 0, v[224:225]
	global_load_dwordx4 v[216:219], v[204:205], off
	global_load_dwordx4 v[220:223], v[130:131], off offset:512
	global_load_dwordx4 v[144:147], v[204:205], off offset:32
	global_load_dwordx4 v[148:151], v[130:131], off offset:544
	global_load_dwordx4 v[152:155], v[204:205], off offset:64
	global_load_dwordx4 v[156:159], v[130:131], off offset:576
	global_load_dwordx4 v[160:163], v[204:205], off offset:96
	global_load_dwordx4 v[164:167], v[130:131], off offset:608
	global_load_dwordx4 v[168:171], v[204:205], off offset:128
	global_load_dwordx4 v[172:175], v[130:131], off offset:640
	global_load_dwordx4 v[176:179], v[204:205], off offset:160
	global_load_dwordx4 v[190:193], v[130:131], off offset:672
	global_load_dwordx4 v[194:197], v[204:205], off offset:192
	global_load_dwordx4 v[198:201], v[130:131], off offset:704
	global_load_dwordx4 v[202:205], v[204:205], off offset:224
	global_load_dwordx4 v[128:131], v[130:131], off offset:736
	v_lshlrev_b32_e32 v136, 3, v0
	v_add_u32_e32 v132, 0, v114
	v_add_u32_e32 v133, s6, v188
	v_add_u32_e32 v3, s5, v188
	ds_read2_b32 v[142:143], v3 offset1:32
	v_lshlrev_b32_e32 v187, 2, v0
	v_lshlrev_b32_e32 v0, 2, v134
	v_and_b32_e32 v0, 12, v0
	v_add_u32_e32 v113, s5, v112
	v_or3_b32 v0, v1, v0, s56
	v_and_or_b32 v16, v2, 3, v187
	v_lshlrev_b32_e32 v17, 1, v0
	ds_read_b128 v[0:3], v113
	ds_read_b128 v[4:7], v113 offset:32
	ds_read_b128 v[108:111], v113 offset:64
	ds_read_b128 v[104:107], v113 offset:96
	v_cmp_gt_u32_e32 vcc, v187, v186
	s_waitcnt lgkmcnt(3)
	v_sub_f32_e32 v8, v142, v0
	v_mul_f32_e32 v8, 0x3fb8aa3b, v8
	v_exp_f32_e32 v8, v8
	v_cmp_lt_u32_e64 s[44:45], v187, v186
	v_sub_f32_e32 v9, v142, v3
	v_mul_f32_e32 v9, 0x3fb8aa3b, v9
	v_mul_f32_e32 v8, v72, v8
	v_cndmask_b32_e64 v18, v8, 0, vcc
	v_sub_f32_e32 v8, v142, v1
	v_mul_f32_e32 v8, 0x3fb8aa3b, v8
	v_exp_f32_e32 v8, v8
	v_exp_f32_e32 v9, v9
	v_sub_f32_e32 v0, v143, v0
	v_sub_f32_e32 v1, v143, v1
	v_mul_f32_e32 v8, v73, v8
	v_cndmask_b32_e64 v19, 0, v8, s[44:45]
	v_sub_f32_e32 v8, v142, v2
	v_mul_f32_e32 v8, 0x3fb8aa3b, v8
	v_exp_f32_e32 v8, v8
	v_mul_f32_e32 v0, 0x3fb8aa3b, v0
	v_mul_f32_e32 v1, 0x3fb8aa3b, v1
	v_exp_f32_e32 v0, v0
	v_exp_f32_e32 v1, v1
	v_sub_f32_e32 v2, v143, v2
	v_sub_f32_e32 v3, v143, v3
	v_mul_f32_e32 v2, 0x3fb8aa3b, v2
	v_mul_f32_e32 v3, 0x3fb8aa3b, v3
	v_pk_mul_f32 v[10:11], v[74:75], v[8:9]
	s_waitcnt lgkmcnt(2)
	v_sub_f32_e32 v8, v142, v4
	v_sub_f32_e32 v9, v142, v5
	v_exp_f32_e32 v2, v2
	v_exp_f32_e32 v3, v3
	v_mul_f32_e32 v8, 0x3fb8aa3b, v8
	v_mul_f32_e32 v9, 0x3fb8aa3b, v9
	v_exp_f32_e32 v8, v8
	v_exp_f32_e32 v9, v9
	v_pk_mul_f32 v[0:1], v[88:89], v[0:1]
	s_waitcnt lgkmcnt(1)
	v_sub_f32_e32 v89, v142, v108
	v_mul_f32_e32 v89, 0x3fb8aa3b, v89
	v_pk_mul_f32 v[2:3], v[90:91], v[2:3]
	v_exp_f32_e32 v90, v89
	v_sub_f32_e32 v89, v142, v109
	v_mul_f32_e32 v89, 0x3fb8aa3b, v89
	v_pk_mul_f32 v[12:13], v[76:77], v[8:9]
	v_sub_f32_e32 v8, v142, v6
	v_sub_f32_e32 v9, v142, v7
	v_exp_f32_e32 v91, v89
	v_mul_f32_e32 v8, 0x3fb8aa3b, v8
	v_mul_f32_e32 v9, 0x3fb8aa3b, v9
	v_exp_f32_e32 v8, v8
	v_exp_f32_e32 v9, v9
	v_pk_mul_f32 v[80:81], v[80:81], v[90:91]
	v_sub_f32_e32 v90, v142, v110
	v_sub_f32_e32 v91, v142, v111
	v_or_b32_e32 v21, 2, v187
	v_mul_f32_e32 v90, 0x3fb8aa3b, v90
	v_mul_f32_e32 v91, 0x3fb8aa3b, v91
	v_or_b32_e32 v20, 3, v187
	v_pk_mul_f32 v[14:15], v[78:79], v[8:9]
	v_cvt_pk_bf16_f32 v9, v10, v11
	v_cmp_le_u32_e64 s[44:45], v21, v186
	v_exp_f32_e32 v90, v90
	v_exp_f32_e32 v91, v91
	v_cndmask_b32_e64 v10, 0, v9, s[44:45]
	v_lshrrev_b32_e32 v9, 16, v9
	v_cmp_le_u32_e64 s[44:45], v20, v186
	v_sub_f32_e32 v4, v143, v4
	v_sub_f32_e32 v5, v143, v5
	v_or_b32_e32 v23, 8, v187
	v_cndmask_b32_e64 v9, 0, v9, s[44:45]
	v_mul_f32_e32 v4, 0x3fb8aa3b, v4
	v_mul_f32_e32 v5, 0x3fb8aa3b, v5
	v_or_b32_e32 v22, 9, v187
	v_perm_b32 v9, v9, v10, s12
	v_cvt_pk_bf16_f32 v10, v12, v13
	v_cmp_le_u32_e64 s[44:45], v23, v186
	v_exp_f32_e32 v4, v4
	v_exp_f32_e32 v5, v5
	v_cndmask_b32_e64 v11, 0, v10, s[44:45]
	v_lshrrev_b32_e32 v10, 16, v10
	v_cmp_le_u32_e64 s[44:45], v22, v186
	v_sub_f32_e32 v6, v143, v6
	v_sub_f32_e32 v7, v143, v7
	v_pk_mul_f32 v[82:83], v[82:83], v[90:91]
	s_waitcnt lgkmcnt(0)
	v_sub_f32_e32 v90, v142, v104
	v_sub_f32_e32 v91, v142, v105
	v_or_b32_e32 v25, 10, v187
	v_cndmask_b32_e64 v10, 0, v10, s[44:45]
	v_mul_f32_e32 v6, 0x3fb8aa3b, v6
	v_mul_f32_e32 v7, 0x3fb8aa3b, v7
	v_mul_f32_e32 v90, 0x3fb8aa3b, v90
	v_mul_f32_e32 v91, 0x3fb8aa3b, v91
	v_or_b32_e32 v24, 11, v187
	v_perm_b32 v10, v10, v11, s12
	v_cvt_pk_bf16_f32 v11, v14, v15
	v_cmp_le_u32_e64 s[44:45], v25, v186
	v_exp_f32_e32 v6, v6
	v_exp_f32_e32 v7, v7
	v_exp_f32_e32 v90, v90
	v_exp_f32_e32 v91, v91
	v_cndmask_b32_e64 v12, 0, v11, s[44:45]
	v_lshrrev_b32_e32 v11, 16, v11
	v_cmp_le_u32_e64 s[44:45], v24, v186
	v_pk_mul_f32 v[4:5], v[92:93], v[4:5]
	v_or_b32_e32 v92, 16, v187
	v_cndmask_b32_e64 v11, 0, v11, s[44:45]
	v_or_b32_e32 v89, 17, v187
	v_cvt_pk_bf16_f32 v80, v80, v81
	v_cmp_le_u32_e64 s[44:45], v92, v186
	v_pk_mul_f32 v[6:7], v[94:95], v[6:7]
	v_or_b32_e32 v94, 18, v187
	v_cndmask_b32_e64 v81, 0, v80, s[44:45]
	v_lshrrev_b32_e32 v80, 16, v80
	v_cmp_le_u32_e64 s[44:45], v89, v186
	v_pk_mul_f32 v[84:85], v[84:85], v[90:91]
	v_sub_f32_e32 v90, v142, v106
	v_sub_f32_e32 v91, v142, v107
	v_cndmask_b32_e64 v80, 0, v80, s[44:45]
	v_or_b32_e32 v93, 19, v187
	v_mul_f32_e32 v90, 0x3fb8aa3b, v90
	v_mul_f32_e32 v91, 0x3fb8aa3b, v91
	v_perm_b32 v80, v80, v81, s12
	v_cvt_pk_bf16_f32 v81, v82, v83
	v_cmp_le_u32_e64 s[44:45], v94, v186
	v_exp_f32_e32 v90, v90
	v_exp_f32_e32 v91, v91
	v_cndmask_b32_e64 v82, 0, v81, s[44:45]
	v_lshrrev_b32_e32 v81, 16, v81
	v_cmp_le_u32_e64 s[44:45], v93, v186
	v_or_b32_e32 v115, 24, v187
	v_or_b32_e32 v95, 25, v187
	v_cndmask_b32_e64 v81, 0, v81, s[44:45]
	v_perm_b32 v81, v81, v82, s12
	v_cvt_pk_bf16_f32 v82, v84, v85
	v_cmp_le_u32_e64 s[44:45], v115, v186
	v_sub_f32_e32 v89, v143, v104
	v_mul_f32_e32 v89, 0x3fb8aa3b, v89
	v_cndmask_b32_e64 v83, 0, v82, s[44:45]
	v_lshrrev_b32_e32 v82, 16, v82
	v_cmp_le_u32_e64 s[44:45], v95, v186
	v_or_b32_e32 v117, 26, v187
	v_pk_mul_f32 v[86:87], v[86:87], v[90:91]
	v_cndmask_b32_e64 v82, 0, v82, s[44:45]
	v_exp_f32_e32 v90, v89
	v_sub_f32_e32 v89, v143, v105
	v_cvt_pk_bf16_f32 v0, v0, v1
	v_cvt_pk_bf16_f32 v1, v2, v3
	v_cvt_pk_bf16_f32 v2, v4, v5
	v_mul_u32_u24_e32 v4, 0x820, v16
	v_or_b32_e32 v116, 27, v187
	v_perm_b32 v82, v82, v83, s12
	v_cvt_pk_bf16_f32 v83, v86, v87
	v_cmp_le_u32_e64 s[44:45], v117, v186
	v_mul_f32_e32 v89, 0x3fb8aa3b, v89
	v_add3_u32 v88, 0, v17, v4
	v_cndmask_b32_e64 v84, 0, v83, s[44:45]
	v_lshrrev_b32_e32 v83, 16, v83
	v_cmp_le_u32_e64 s[44:45], v116, v186
	v_exp_f32_e32 v91, v89
	v_sub_f32_e32 v89, v143, v106
	v_cvt_pk_bf16_f32 v3, v6, v7
	ds_read_b64_tr_b16 v[4:5], v88
	ds_read_b64_tr_b16 v[6:7], v88 offset:16640
	v_cndmask_b32_e64 v83, 0, v83, s[44:45]
	v_mul_f32_e32 v89, 0x3fb8aa3b, v89
	v_perm_b32 v83, v83, v84, s12
	v_sub_f32_e32 v84, v143, v108
	v_sub_f32_e32 v85, v143, v109
	v_sub_f32_e32 v86, v143, v110
	v_sub_f32_e32 v87, v143, v111
	v_exp_f32_e32 v92, v89
	v_sub_f32_e32 v89, v143, v107
	v_mul_f32_e32 v84, 0x3fb8aa3b, v84
	v_mul_f32_e32 v85, 0x3fb8aa3b, v85
	v_mul_f32_e32 v86, 0x3fb8aa3b, v86
	v_mul_f32_e32 v87, 0x3fb8aa3b, v87
	v_mul_f32_e32 v89, 0x3fb8aa3b, v89
	v_exp_f32_e32 v84, v84
	v_exp_f32_e32 v85, v85
	v_exp_f32_e32 v86, v86
	v_exp_f32_e32 v87, v87
	v_exp_f32_e32 v93, v89
	v_cvt_pk_bf16_f32 v8, v18, v19
	v_perm_b32 v11, v11, v12, s12
	s_waitcnt lgkmcnt(0)
	v_mfma_f32_32x32x16_bf16 v[16:31], v[4:7], v[0:3], 0
	v_mul_f32_e64 v84, v96, v84
	v_mul_f32_e64 v85, v97, v85
	v_mul_f32_e64 v86, v98, v86
	v_mul_f32_e64 v87, v99, v87
	v_mul_f32_e64 v90, v100, v90
	v_mul_f32_e64 v91, v101, v91
	v_pk_mul_f32 v[92:93], v[102:103], v[92:93]
	v_cvt_pk_bf16_f32 v84, v84, v85
	v_cvt_pk_bf16_f32 v85, v86, v87
	v_cvt_pk_bf16_f32 v86, v90, v91
	v_mfma_f32_32x32x16_bf16 v[64:79], v[4:7], v[8:11], 0
	ds_read_b64_tr_b16 v[4:5], v88 offset:64
	ds_read_b64_tr_b16 v[6:7], v88 offset:16704
	v_cvt_pk_bf16_f32 v87, v92, v93
	ds_read_b64_tr_b16 v[90:91], v88 offset:33280
	ds_read_b64_tr_b16 v[92:93], v88 offset:49920
	v_or_b32_e32 v89, 33, v187
	s_add_u32 s2, s2, s16
	s_addc_u32 s3, s3, s17
	s_waitcnt lgkmcnt(2)
	v_mfma_f32_32x32x16_bf16 v[32:47], v[4:7], v[8:11], 0
	v_mfma_f32_32x32x16_bf16 v[0:15], v[4:7], v[0:3], 0
	s_waitcnt lgkmcnt(0)
	v_mfma_f32_32x32x16_bf16 v[64:79], v[90:93], v[80:83], v[64:79]
	v_mfma_f32_32x32x16_bf16 v[16:31], v[90:93], v[84:87], v[16:31]
	ds_read_b64_tr_b16 v[90:91], v88 offset:33344
	ds_read_b64_tr_b16 v[92:93], v88 offset:49984
	s_waitcnt lgkmcnt(0)
	v_mfma_f32_32x32x16_bf16 v[32:47], v[90:93], v[80:83], v[32:47]
	v_mfma_f32_32x32x16_bf16 v[0:15], v[90:93], v[84:87], v[0:15]
	ds_read_b128 v[90:93], v113 offset:128
	ds_read_b128 v[94:97], v113 offset:160
	ds_read_b128 v[84:87], v113 offset:192
	ds_read_b128 v[80:83], v113 offset:224
	s_waitcnt lgkmcnt(3)
	v_sub_f32_e32 v90, v143, v90
	v_mul_f32_e32 v90, 0x3fb8aa3b, v90
	v_exp_f32_e32 v90, v90
	s_nop 0
	v_mul_f32_e32 v48, v48, v90
	v_cndmask_b32_e64 v98, v48, 0, vcc
	v_sub_f32_e32 v48, v143, v91
	v_mul_f32_e32 v48, 0x3fb8aa3b, v48
	v_exp_f32_e32 v48, v48
	v_cmp_le_u32_e32 vcc, v89, v185
	v_mul_f32_e32 v48, v49, v48
	s_nop 0
	v_cndmask_b32_e32 v89, 0, v48, vcc
	v_sub_f32_e32 v48, v143, v92
	v_sub_f32_e32 v49, v143, v93
	v_mul_f32_e32 v48, 0x3fb8aa3b, v48
	v_mul_f32_e32 v49, 0x3fb8aa3b, v49
	v_exp_f32_e32 v48, v48
	v_exp_f32_e32 v49, v49
	v_or_b32_e32 v93, 34, v187
	v_or_b32_e32 v92, 35, v187
	v_cmp_le_u32_e32 vcc, v93, v185
	v_pk_mul_f32 v[48:49], v[50:51], v[48:49]
	s_waitcnt lgkmcnt(2)
	v_sub_f32_e32 v50, v143, v94
	v_sub_f32_e32 v51, v143, v95
	v_mul_f32_e32 v50, 0x3fb8aa3b, v50
	v_mul_f32_e32 v51, 0x3fb8aa3b, v51
	v_exp_f32_e32 v50, v50
	v_exp_f32_e32 v51, v51
	v_cvt_pk_bf16_f32 v48, v48, v49
	v_cndmask_b32_e32 v49, 0, v48, vcc
	v_lshrrev_b32_e32 v48, 16, v48
	v_pk_mul_f32 v[50:51], v[52:53], v[50:51]
	v_sub_f32_e32 v52, v143, v96
	v_sub_f32_e32 v53, v143, v97
	v_mul_f32_e32 v52, 0x3fb8aa3b, v52
	v_mul_f32_e32 v53, 0x3fb8aa3b, v53
	v_exp_f32_e32 v52, v52
	v_exp_f32_e32 v53, v53
	v_cmp_le_u32_e32 vcc, v92, v185
	v_or_b32_e32 v95, 40, v187
	v_or_b32_e32 v94, 41, v187
	v_cndmask_b32_e32 v48, 0, v48, vcc
	v_pk_mul_f32 v[90:91], v[54:55], v[52:53]
	v_perm_b32 v53, v48, v49, s12
	v_cvt_pk_bf16_f32 v48, v50, v51
	v_cmp_le_u32_e32 vcc, v95, v185
	v_or_b32_e32 v97, 42, v187
	v_or_b32_e32 v96, 43, v187
	v_cndmask_b32_e32 v49, 0, v48, vcc
	v_lshrrev_b32_e32 v48, 16, v48
	v_cmp_le_u32_e32 vcc, v94, v185
	v_cvt_pk_bf16_f32 v52, v98, v89
	v_add_u32_e32 v89, 0x10440, v88
	v_cndmask_b32_e32 v48, 0, v48, vcc
	v_perm_b32 v54, v48, v49, s12
	v_cvt_pk_bf16_f32 v48, v90, v91
	v_cmp_le_u32_e32 vcc, v97, v185
	s_nop 1
	v_cndmask_b32_e32 v49, 0, v48, vcc
	v_lshrrev_b32_e32 v48, 16, v48
	v_cmp_le_u32_e32 vcc, v96, v185
	s_nop 1
	v_cndmask_b32_e32 v48, 0, v48, vcc
	v_perm_b32 v55, v48, v49, s12
	v_add_u32_e32 v48, 0x10400, v88
	v_add_u32_e32 v49, 0x14500, v88
	ds_read_b64_tr_b16 v[90:91], v48
	ds_read_b64_tr_b16 v[92:93], v49
	v_mov_b64_e32 v[48:49], s[48:49]
	v_mov_b64_e32 v[50:51], s[50:51]
	s_waitcnt lgkmcnt(0)
	v_mfma_f32_32x32x16_bf16 v[16:31], v[90:93], v[52:55], v[16:31]
	v_mfma_f32_32x32x16_bf16 v[64:79], v[90:93], v[48:51], v[64:79]
	v_add_u32_e32 v92, 0x14540, v88
	ds_read_b64_tr_b16 v[90:91], v89
	ds_read_b64_tr_b16 v[92:93], v92
	s_waitcnt lgkmcnt(0)
	v_mfma_f32_32x32x16_bf16 v[0:15], v[90:93], v[52:55], v[0:15]
	v_sub_f32_e32 v52, v143, v84
	v_sub_f32_e32 v53, v143, v85
	v_mul_f32_e32 v52, 0x3fb8aa3b, v52
	v_mul_f32_e32 v53, 0x3fb8aa3b, v53
	v_exp_f32_e32 v52, v52
	v_exp_f32_e32 v53, v53
	v_sub_f32_e32 v54, v143, v86
	v_sub_f32_e32 v55, v143, v87
	v_mul_f32_e32 v54, 0x3fb8aa3b, v54
	v_mul_f32_e32 v55, 0x3fb8aa3b, v55
	v_exp_f32_e32 v54, v54
	v_exp_f32_e32 v55, v55
	v_or_b32_e32 v85, 48, v187
	v_pk_mul_f32 v[52:53], v[56:57], v[52:53]
	v_sub_f32_e32 v56, v143, v80
	v_sub_f32_e32 v57, v143, v81
	v_or_b32_e32 v84, 49, v187
	v_mul_f32_e32 v56, 0x3fb8aa3b, v56
	v_mul_f32_e32 v57, 0x3fb8aa3b, v57
	v_cvt_pk_bf16_f32 v52, v52, v53
	v_cmp_le_u32_e32 vcc, v85, v185
	v_exp_f32_e32 v56, v56
	v_exp_f32_e32 v57, v57
	v_cndmask_b32_e32 v53, 0, v52, vcc
	v_lshrrev_b32_e32 v52, 16, v52
	v_cmp_le_u32_e32 vcc, v84, v185
	v_or_b32_e32 v87, 50, v187
	v_pk_mul_f32 v[54:55], v[58:59], v[54:55]
	v_sub_f32_e32 v58, v143, v82
	v_sub_f32_e32 v59, v143, v83
	v_cndmask_b32_e32 v52, 0, v52, vcc
	v_or_b32_e32 v86, 51, v187
	v_mul_f32_e32 v58, 0x3fb8aa3b, v58
	v_mul_f32_e32 v59, 0x3fb8aa3b, v59
	v_perm_b32 v52, v52, v53, s12
	v_cvt_pk_bf16_f32 v53, v54, v55
	v_cmp_le_u32_e32 vcc, v87, v185
	v_exp_f32_e32 v58, v58
	v_exp_f32_e32 v59, v59
	v_cndmask_b32_e32 v54, 0, v53, vcc
	v_lshrrev_b32_e32 v53, 16, v53
	v_cmp_le_u32_e32 vcc, v86, v185
	v_or_b32_e32 v81, 56, v187
	v_pk_mul_f32 v[56:57], v[60:61], v[56:57]
	v_cndmask_b32_e32 v53, 0, v53, vcc
	v_or_b32_e32 v80, 57, v187
	v_perm_b32 v53, v53, v54, s12
	v_cvt_pk_bf16_f32 v54, v56, v57
	v_cmp_le_u32_e32 vcc, v81, v185
	v_or_b32_e32 v61, 58, v187
	v_pk_mul_f32 v[58:59], v[62:63], v[58:59]
	v_cndmask_b32_e32 v55, 0, v54, vcc
	v_lshrrev_b32_e32 v54, 16, v54
	v_cmp_le_u32_e32 vcc, v80, v185
	v_or_b32_e32 v60, 59, v187
	v_mfma_f32_32x32x16_bf16 v[32:47], v[90:93], v[48:51], v[32:47]
	v_cndmask_b32_e32 v54, 0, v54, vcc
	v_perm_b32 v54, v54, v55, s12
	v_cvt_pk_bf16_f32 v55, v58, v59
	v_cmp_le_u32_e32 vcc, v61, v185
	v_add_u32_e32 v58, 0x1c700, v88
	s_nop 0
	v_cndmask_b32_e32 v56, 0, v55, vcc
	v_lshrrev_b32_e32 v55, 16, v55
	v_cmp_le_u32_e32 vcc, v60, v185
	s_nop 1
	v_cndmask_b32_e32 v55, 0, v55, vcc
	v_perm_b32 v55, v55, v56, s12
	v_add_u32_e32 v56, 0x18600, v88
	ds_read_b64_tr_b16 v[56:57], v56
	ds_read_b64_tr_b16 v[58:59], v58
	s_waitcnt lgkmcnt(0)
	v_mfma_f32_32x32x16_bf16 v[64:79], v[56:59], v[48:51], v[64:79]
	v_mfma_f32_32x32x16_bf16 v[16:31], v[56:59], v[52:55], v[16:31]
	v_add_u32_e32 v56, 0x18640, v88
	v_add_u32_e32 v58, 0x1c740, v88
	ds_read_b64_tr_b16 v[56:57], v56
	ds_read_b64_tr_b16 v[58:59], v58
	s_waitcnt lgkmcnt(0)
	v_mfma_f32_32x32x16_bf16 v[32:47], v[56:59], v[48:51], v[32:47]
	v_mfma_f32_32x32x16_bf16 v[0:15], v[56:59], v[52:55], v[0:15]
	v_mov_b32_e32 v113, v137
	v_lshl_add_u64 v[48:49], s[2:3], 0, v[112:113]
	v_lshlrev_b32_e32 v50, 8, v186
	v_mov_b32_e32 v51, v137
	v_lshl_add_u64 v[52:53], v[48:49], 0, v[50:51]
	s_mov_b64 s[2:3], 0x1797e200
	v_lshl_add_u64 v[56:57], v[52:53], 0, s[2:3]
	s_mov_b32 s2, 0x1797e000
	v_add_co_u32_e32 v48, vcc, s2, v52
	s_mov_b32 s2, 0x17980000
	s_nop 0
	v_addc_co_u32_e32 v49, vcc, 0, v53, vcc
	v_add_co_u32_e32 v58, vcc, s2, v52
	s_nop 0
	v_addc_co_u32_e32 v59, vcc, 0, v53, vcc
	s_add_i32 s4, s4, 0
	v_add3_u32 v134, s4, v112, v114
	v_add_u32_e32 v135, 0x10400, v134
	s_waitcnt vmcnt(15)
	s_waitcnt vmcnt(14)
	s_waitcnt vmcnt(13)
	s_waitcnt vmcnt(12)
	s_waitcnt vmcnt(11)
	s_waitcnt vmcnt(10)
	s_waitcnt vmcnt(9)
	s_waitcnt vmcnt(8)
	s_waitcnt vmcnt(7)
	s_waitcnt vmcnt(6)
	s_waitcnt vmcnt(5)
	s_waitcnt vmcnt(4)
	s_waitcnt vmcnt(3)
	s_waitcnt vmcnt(2)
	s_waitcnt vmcnt(1)
	s_waitcnt vmcnt(0)
	ds_read_b128 v[56:59], v134 offset:1536
	ds_read_b128 v[206:209], v134 offset:1568
	ds_read_b128 v[60:63], v135 offset:1536
	ds_read_b128 v[210:213], v135 offset:1568
	s_waitcnt lgkmcnt(3)
	v_mfma_f32_32x32x16_bf16 v[112:127], v[216:219], v[56:59], 0
	s_waitcnt lgkmcnt(1)
	v_mfma_f32_32x32x16_bf16 v[80:95], v[216:219], v[60:63], 0
	v_mfma_f32_32x32x16_bf16 v[96:111], v[220:223], v[56:59], 0
	v_mfma_f32_32x32x16_bf16 v[48:63], v[220:223], v[60:63], 0
	s_load_dwordx2 s[2:3], s[0:1], 0x70
	v_or_b32_e32 v214, s15, v186
	v_ashrrev_i32_e32 v215, 31, v214
	v_lshlrev_b64 v[214:215], 10, v[214:215]
	v_or_b32_e32 v216, s15, v185
	v_ashrrev_i32_e32 v217, 31, v216
	v_lshlrev_b64 v[216:217], 10, v[216:217]
	s_ashr_i32 s57, s56, 31
	s_lshl_b64 s[4:5], s[56:57], 1
	s_add_u32 s4, s54, s4
	s_addc_u32 s5, s55, s5
	v_lshl_add_u64 v[218:219], s[4:5], 0, v[136:137]
	s_mov_b64 s[4:5], 0xd6fe200
	v_lshl_add_u64 v[218:219], v[218:219], 0, s[4:5]
	v_lshl_add_u64 v[214:215], v[218:219], 0, v[214:215]
	v_lshl_add_u64 v[216:217], v[218:219], 0, v[216:217]
	s_waitcnt lgkmcnt(0)
	s_add_u32 s2, s2, s36
	s_addc_u32 s3, s3, s37
	global_load_dword v189, v137, s[2:3]
	global_load_dwordx2 v[250:251], v[214:215], off
	global_load_dwordx2 v[248:249], v[214:215], off offset:16
	global_load_dwordx2 v[246:247], v[214:215], off offset:32
	global_load_dwordx2 v[244:245], v[214:215], off offset:48
	global_load_dwordx2 v[242:243], v[214:215], off offset:64
	global_load_dwordx2 v[240:241], v[214:215], off offset:80
	global_load_dwordx2 v[238:239], v[214:215], off offset:96
	global_load_dwordx2 v[236:237], v[214:215], off offset:112
	global_load_dwordx2 v[234:235], v[216:217], off
	global_load_dwordx2 v[232:233], v[216:217], off offset:16
	global_load_dwordx2 v[230:231], v[216:217], off offset:32
	global_load_dwordx2 v[228:229], v[216:217], off offset:48
	global_load_dwordx2 v[226:227], v[216:217], off offset:64
	global_load_dwordx2 v[224:225], v[216:217], off offset:80
	global_load_dwordx2 v[222:223], v[216:217], off offset:96
	global_load_dwordx2 v[220:221], v[216:217], off offset:112
	v_mfma_f32_32x32x16_bf16 v[112:127], v[144:147], v[206:209], v[112:127]
	s_waitcnt lgkmcnt(0)
	v_mfma_f32_32x32x16_bf16 v[80:95], v[144:147], v[210:213], v[80:95]
	ds_read_b128 v[144:147], v134 offset:1600
	v_mfma_f32_32x32x16_bf16 v[96:111], v[148:151], v[206:209], v[96:111]
	v_mfma_f32_32x32x16_bf16 v[48:63], v[148:151], v[210:213], v[48:63]
	ds_read_b128 v[148:151], v135 offset:1600
	s_waitcnt lgkmcnt(1)
	v_mfma_f32_32x32x16_bf16 v[112:127], v[152:155], v[144:147], v[112:127]
	s_waitcnt lgkmcnt(0)
	v_mfma_f32_32x32x16_bf16 v[80:95], v[152:155], v[148:151], v[80:95]
	v_mfma_f32_32x32x16_bf16 v[96:111], v[156:159], v[144:147], v[96:111]
	ds_read_b128 v[144:147], v134 offset:1632
	v_mfma_f32_32x32x16_bf16 v[48:63], v[156:159], v[148:151], v[48:63]
	ds_read_b128 v[148:151], v135 offset:1632
	s_waitcnt lgkmcnt(1)
	v_mfma_f32_32x32x16_bf16 v[112:127], v[160:163], v[144:147], v[112:127]
	s_waitcnt lgkmcnt(0)
	v_mfma_f32_32x32x16_bf16 v[80:95], v[160:163], v[148:151], v[80:95]
	v_mfma_f32_32x32x16_bf16 v[96:111], v[164:167], v[144:147], v[96:111]
	ds_read_b128 v[144:147], v134 offset:1664
	v_mfma_f32_32x32x16_bf16 v[48:63], v[164:167], v[148:151], v[48:63]
	ds_read_b128 v[148:151], v135 offset:1664
	s_waitcnt lgkmcnt(1)
	v_mfma_f32_32x32x16_bf16 v[112:127], v[168:171], v[144:147], v[112:127]
	s_waitcnt lgkmcnt(0)
	v_mfma_f32_32x32x16_bf16 v[80:95], v[168:171], v[148:151], v[80:95]
	v_mfma_f32_32x32x16_bf16 v[96:111], v[172:175], v[144:147], v[96:111]
	ds_read_b128 v[144:147], v134 offset:1696
	v_mfma_f32_32x32x16_bf16 v[48:63], v[172:175], v[148:151], v[48:63]
	ds_read_b128 v[148:151], v135 offset:1696
	s_waitcnt lgkmcnt(1)
	v_mfma_f32_32x32x16_bf16 v[112:127], v[176:179], v[144:147], v[112:127]
	s_waitcnt lgkmcnt(0)
	v_mfma_f32_32x32x16_bf16 v[80:95], v[176:179], v[148:151], v[80:95]
	v_mfma_f32_32x32x16_bf16 v[96:111], v[190:193], v[144:147], v[96:111]
	ds_read_b128 v[144:147], v134 offset:1728
	v_mfma_f32_32x32x16_bf16 v[48:63], v[190:193], v[148:151], v[48:63]
	ds_read_b128 v[148:151], v135 offset:1728
	s_waitcnt lgkmcnt(1)
	v_mfma_f32_32x32x16_bf16 v[112:127], v[194:197], v[144:147], v[112:127]
	s_waitcnt lgkmcnt(0)
	v_mfma_f32_32x32x16_bf16 v[80:95], v[194:197], v[148:151], v[80:95]
	v_mfma_f32_32x32x16_bf16 v[96:111], v[198:201], v[144:147], v[96:111]
	ds_read_b128 v[144:147], v134 offset:1760
	v_mfma_f32_32x32x16_bf16 v[48:63], v[198:201], v[148:151], v[48:63]
	ds_read_b128 v[148:151], v135 offset:1760
	v_mul_f32_e32 v134, 0x3fb8aa3b, v142
	v_exp_f32_e32 v142, v134
	s_waitcnt lgkmcnt(1)
	v_mfma_f32_32x32x16_bf16 v[112:127], v[202:205], v[144:147], v[112:127]
	s_waitcnt lgkmcnt(0)
	v_mfma_f32_32x32x16_bf16 v[80:95], v[202:205], v[148:151], v[80:95]
	v_mfma_f32_32x32x16_bf16 v[96:111], v[128:131], v[144:147], v[96:111]
	v_mfma_f32_32x32x16_bf16 v[48:63], v[128:131], v[148:151], v[48:63]
	v_or_b32_e32 v144, s15, v186
	v_ashrrev_i32_e32 v145, 31, v144
	v_lshlrev_b64 v[130:131], 10, v[144:145]
	v_or_b32_e32 v140, s15, v185
	s_waitcnt lgkmcnt(0)
	s_ashr_i32 s57, s56, 31
	s_lshl_b64 s[4:5], s[56:57], 1
	s_add_u32 s2, s54, s4
	s_addc_u32 s3, s55, s5
	v_lshl_add_u64 v[128:129], s[2:3], 0, v[136:137]
	s_mov_b64 s[2:3], 0xd6fe200
	v_lshl_add_u64 v[128:129], v[128:129], 0, s[2:3]
	v_lshl_add_u64 v[130:131], v[128:129], 0, v[130:131]
	v_ashrrev_i32_e32 v141, 31, v140
	v_lshlrev_b64 v[130:131], 10, v[140:141]
	v_lshl_add_u64 v[128:129], v[128:129], 0, v[130:131]
	v_add_u32_e32 v128, 0x20800, v133
	v_pk_fma_f32 v[64:65], v[142:143], v[112:113], v[64:65] op_sel_hi:[0,1,1]
	v_pk_fma_f32 v[66:67], v[142:143], v[114:115], v[66:67] op_sel_hi:[0,1,1]
	v_pk_fma_f32 v[68:69], v[142:143], v[116:117], v[68:69] op_sel_hi:[0,1,1]
	v_pk_fma_f32 v[70:71], v[142:143], v[118:119], v[70:71] op_sel_hi:[0,1,1]
	v_pk_fma_f32 v[72:73], v[142:143], v[120:121], v[72:73] op_sel_hi:[0,1,1]
	v_pk_fma_f32 v[74:75], v[142:143], v[122:123], v[74:75] op_sel_hi:[0,1,1]
	v_pk_fma_f32 v[76:77], v[142:143], v[124:125], v[76:77] op_sel_hi:[0,1,1]
	v_pk_fma_f32 v[78:79], v[142:143], v[126:127], v[78:79] op_sel_hi:[0,1,1]
	v_pk_fma_f32 v[32:33], v[142:143], v[96:97], v[32:33] op_sel_hi:[0,1,1]
	v_pk_fma_f32 v[34:35], v[142:143], v[98:99], v[34:35] op_sel_hi:[0,1,1]
	v_pk_fma_f32 v[36:37], v[142:143], v[100:101], v[36:37] op_sel_hi:[0,1,1]
	v_pk_fma_f32 v[38:39], v[142:143], v[102:103], v[38:39] op_sel_hi:[0,1,1]
	v_pk_fma_f32 v[40:41], v[142:143], v[104:105], v[40:41] op_sel_hi:[0,1,1]
	v_pk_fma_f32 v[42:43], v[142:143], v[106:107], v[42:43] op_sel_hi:[0,1,1]
	v_pk_fma_f32 v[44:45], v[142:143], v[108:109], v[44:45] op_sel_hi:[0,1,1]
	v_pk_fma_f32 v[46:47], v[142:143], v[110:111], v[46:47] op_sel_hi:[0,1,1]
	s_add_i32 s6, s6, 0x21800
	s_waitcnt vmcnt(15)
	s_waitcnt vmcnt(14)
	s_waitcnt vmcnt(13)
	s_waitcnt vmcnt(12)
	s_waitcnt vmcnt(11)
	s_waitcnt vmcnt(10)
	s_waitcnt vmcnt(9)
	s_waitcnt vmcnt(8)
	s_waitcnt vmcnt(7)
	s_waitcnt vmcnt(6)
	s_waitcnt vmcnt(5)
	s_waitcnt vmcnt(4)
	s_waitcnt vmcnt(3)
	s_waitcnt vmcnt(2)
	s_waitcnt vmcnt(1)
	s_waitcnt vmcnt(0)
	ds_read2_b32 v[162:163], v128 offset1:32
	v_lshlrev_b32_e32 v190, 16, v250
	v_and_b32_e32 v191, 0xffff0000, v250
	s_waitcnt lgkmcnt(0)
	v_div_scale_f32 v128, s[2:3], v162, v162, v189
	v_rcp_f32_e32 v129, v128
	s_lshl_b32 s2, s56, 1
	v_add3_u32 v136, v132, v136, s2
	v_fma_f32 v130, -v128, v129, 1.0
	v_fmac_f32_e32 v129, v130, v129
	v_div_scale_f32 v130, vcc, v189, v162, v189
	v_mul_f32_e32 v131, v130, v129
	v_fma_f32 v133, -v128, v131, v130
	v_fmac_f32_e32 v131, v133, v129
	v_fma_f32 v128, -v128, v131, v130
	v_div_fmas_f32 v128, v128, v129, v131
	v_div_fixup_f32 v162, v128, v162, v189
	ds_read2_b64 v[132:135], v136 offset1:2
	ds_read2_b64 v[128:131], v136 offset0:4 offset1:6
	s_waitcnt lgkmcnt(1)
	v_lshlrev_b32_e32 v112, 16, v132
	v_and_b32_e32 v113, 0xffff0000, v132
	v_mul_f32_e32 v132, 0xbfb8aa3b, v190
	v_exp_f32_e32 v132, v132
	v_lshlrev_b32_e32 v114, 16, v133
	v_and_b32_e32 v115, 0xffff0000, v133
	v_and_b32_e32 v133, 0xffff0000, v251
	v_add_f32_e32 v132, 1.0, v132
	v_rcp_f32_e32 v192, v132
	v_lshlrev_b32_e32 v132, 16, v251
	v_mul_f32_e32 v178, 0xbfb8aa3b, v132
	v_pk_fma_f32 v[66:67], v[162:163], v[114:115], v[66:67] op_sel_hi:[0,1,1]
	v_mul_f32_e32 v114, 0xbfb8aa3b, v133
	v_exp_f32_e32 v178, v178
	v_exp_f32_e32 v114, v114
	v_lshlrev_b32_e32 v116, 16, v134
	v_and_b32_e32 v117, 0xffff0000, v134
	v_add_f32_e32 v178, 1.0, v178
	v_add_f32_e32 v114, 1.0, v114
	v_rcp_f32_e32 v178, v178
	v_rcp_f32_e32 v179, v114
	v_pk_fma_f32 v[68:69], v[162:163], v[116:117], v[68:69] op_sel_hi:[0,1,1]
	v_lshlrev_b32_e32 v118, 16, v135
	v_and_b32_e32 v119, 0xffff0000, v135
	v_pk_mul_f32 v[114:115], v[178:179], v[132:133]
	v_lshlrev_b32_e32 v132, 16, v248
	v_and_b32_e32 v133, 0xffff0000, v248
	v_mul_f32_e32 v134, 0xbfb8aa3b, v132
	v_mul_f32_e32 v116, 0xbfb8aa3b, v133
	v_exp_f32_e32 v134, v134
	v_exp_f32_e32 v116, v116
	v_pk_fma_f32 v[70:71], v[162:163], v[118:119], v[70:71] op_sel_hi:[0,1,1]
	s_waitcnt lgkmcnt(0)
	v_lshlrev_b32_e32 v120, 16, v128
	v_add_f32_e32 v134, 1.0, v134
	v_add_f32_e32 v116, 1.0, v116
	v_rcp_f32_e32 v178, v134
	v_rcp_f32_e32 v179, v116
	v_and_b32_e32 v121, 0xffff0000, v128
	v_pk_fma_f32 v[72:73], v[162:163], v[120:121], v[72:73] op_sel_hi:[0,1,1]
	v_lshlrev_b32_e32 v122, 16, v129
	v_pk_mul_f32 v[116:117], v[178:179], v[132:133]
	v_lshlrev_b32_e32 v132, 16, v249
	v_and_b32_e32 v133, 0xffff0000, v249
	v_mul_f32_e32 v134, 0xbfb8aa3b, v132
	v_mul_f32_e32 v118, 0xbfb8aa3b, v133
	v_exp_f32_e32 v134, v134
	v_exp_f32_e32 v118, v118
	v_and_b32_e32 v123, 0xffff0000, v129
	v_and_b32_e32 v129, 0xffff0000, v247
	v_add_f32_e32 v134, 1.0, v134
	v_add_f32_e32 v118, 1.0, v118
	v_rcp_f32_e32 v134, v134
	v_rcp_f32_e32 v135, v118
	v_pk_fma_f32 v[74:75], v[162:163], v[122:123], v[74:75] op_sel_hi:[0,1,1]
	v_mul_f32_e32 v122, 0xbfb8aa3b, v129
	v_exp_f32_e32 v122, v122
	v_pk_mul_f32 v[118:119], v[134:135], v[132:133]
	v_lshlrev_b32_e32 v132, 16, v246
	v_and_b32_e32 v133, 0xffff0000, v246
	v_mul_f32_e32 v128, 0xbfb8aa3b, v132
	v_mul_f32_e32 v120, 0xbfb8aa3b, v133
	v_exp_f32_e32 v128, v128
	v_exp_f32_e32 v120, v120
	v_add_f32_e32 v122, 1.0, v122
	v_lshlrev_b32_e32 v124, 16, v130
	v_add_f32_e32 v128, 1.0, v128
	v_add_f32_e32 v120, 1.0, v120
	v_rcp_f32_e32 v134, v128
	v_rcp_f32_e32 v135, v120
	v_lshlrev_b32_e32 v128, 16, v247
	v_and_b32_e32 v125, 0xffff0000, v130
	v_pk_fma_f32 v[76:77], v[162:163], v[124:125], v[76:77] op_sel_hi:[0,1,1]
	v_pk_mul_f32 v[120:121], v[134:135], v[132:133]
	v_mul_f32_e32 v132, 0xbfb8aa3b, v128
	v_exp_f32_e32 v132, v132
	v_rcp_f32_e32 v133, v122
	v_lshlrev_b32_e32 v126, 16, v131
	v_and_b32_e32 v127, 0xffff0000, v131
	v_add_f32_e32 v132, 1.0, v132
	v_rcp_f32_e32 v132, v132
	v_pk_fma_f32 v[78:79], v[162:163], v[126:127], v[78:79] op_sel_hi:[0,1,1]
	v_pk_fma_f32 v[64:65], v[162:163], v[112:113], v[64:65] op_sel_hi:[0,1,1]
	v_mul_f32_e32 v112, 0xbfb8aa3b, v191
	v_pk_mul_f32 v[122:123], v[132:133], v[128:129]
	v_lshlrev_b32_e32 v128, 16, v244
	v_and_b32_e32 v129, 0xffff0000, v244
	v_mul_f32_e32 v130, 0xbfb8aa3b, v128
	v_mul_f32_e32 v124, 0xbfb8aa3b, v129
	v_exp_f32_e32 v130, v130
	v_exp_f32_e32 v124, v124
	v_exp_f32_e32 v112, v112
	v_pk_mul_f32 v[66:67], v[114:115], v[66:67]
	v_add_f32_e32 v130, 1.0, v130
	v_add_f32_e32 v124, 1.0, v124
	v_rcp_f32_e32 v132, v130
	v_rcp_f32_e32 v133, v124
	v_add_f32_e32 v112, 1.0, v112
	v_rcp_f32_e32 v193, v112
	v_pk_mul_f32 v[114:115], v[66:67], v[66:67]
	v_pk_mul_f32 v[124:125], v[132:133], v[128:129]
	v_lshlrev_b32_e32 v128, 16, v245
	v_and_b32_e32 v129, 0xffff0000, v245
	v_mul_f32_e32 v130, 0xbfb8aa3b, v128
	v_mul_f32_e32 v126, 0xbfb8aa3b, v129
	v_exp_f32_e32 v130, v130
	v_exp_f32_e32 v126, v126
	v_lshlrev_b32_e32 v132, 16, v242
	v_and_b32_e32 v133, 0xffff0000, v242
	v_add_f32_e32 v130, 1.0, v130
	v_add_f32_e32 v126, 1.0, v126
	v_rcp_f32_e32 v130, v130
	v_rcp_f32_e32 v131, v126
	v_pk_mul_f32 v[112:113], v[192:193], v[190:191]
	v_pk_mul_f32 v[68:69], v[116:117], v[68:69]
	v_pk_mul_f32 v[64:65], v[112:113], v[64:65]
	v_pk_mul_f32 v[126:127], v[130:131], v[128:129]
	ds_read2_b64 v[128:131], v136 offset0:8 offset1:10
	v_pk_mul_f32 v[112:113], v[64:65], v[64:65]
	v_pk_mul_f32 v[116:117], v[68:69], v[68:69]
	v_add_f32_e32 v112, v112, v113
	v_add_f32_e32 v112, v114, v112
	s_waitcnt lgkmcnt(0)
	v_lshlrev_b32_e32 v96, 16, v128
	v_and_b32_e32 v97, 0xffff0000, v128
	v_mul_f32_e32 v128, 0xbfb8aa3b, v132
	v_pk_fma_f32 v[32:33], v[162:163], v[96:97], v[32:33] op_sel_hi:[0,1,1]
	v_mul_f32_e32 v96, 0xbfb8aa3b, v133
	v_exp_f32_e32 v128, v128
	v_exp_f32_e32 v96, v96
	v_lshlrev_b32_e32 v98, 16, v129
	v_and_b32_e32 v99, 0xffff0000, v129
	v_add_f32_e32 v128, 1.0, v128
	v_add_f32_e32 v96, 1.0, v96
	v_rcp_f32_e32 v134, v128
	v_rcp_f32_e32 v135, v96
	v_lshlrev_b32_e32 v128, 16, v243
	v_and_b32_e32 v129, 0xffff0000, v243
	v_pk_fma_f32 v[34:35], v[162:163], v[98:99], v[34:35] op_sel_hi:[0,1,1]
	v_pk_mul_f32 v[96:97], v[134:135], v[132:133]
	v_mul_f32_e32 v132, 0xbfb8aa3b, v128
	v_mul_f32_e32 v98, 0xbfb8aa3b, v129
	v_exp_f32_e32 v132, v132
	v_exp_f32_e32 v98, v98
	v_lshlrev_b32_e32 v100, 16, v130
	v_and_b32_e32 v101, 0xffff0000, v130
	v_add_f32_e32 v132, 1.0, v132
	v_add_f32_e32 v98, 1.0, v98
	v_rcp_f32_e32 v132, v132
	v_rcp_f32_e32 v133, v98
	v_pk_fma_f32 v[36:37], v[162:163], v[100:101], v[36:37] op_sel_hi:[0,1,1]
	v_lshlrev_b32_e32 v102, 16, v131
	v_and_b32_e32 v103, 0xffff0000, v131
	v_pk_mul_f32 v[98:99], v[132:133], v[128:129]
	v_lshlrev_b32_e32 v128, 16, v240
	v_and_b32_e32 v129, 0xffff0000, v240
	v_mul_f32_e32 v130, 0xbfb8aa3b, v128
	v_mul_f32_e32 v100, 0xbfb8aa3b, v129
	v_exp_f32_e32 v130, v130
	v_exp_f32_e32 v100, v100
	v_pk_fma_f32 v[38:39], v[162:163], v[102:103], v[38:39] op_sel_hi:[0,1,1]
	v_add_f32_e32 v112, v115, v112
	v_add_f32_e32 v130, 1.0, v130
	v_add_f32_e32 v100, 1.0, v100
	v_rcp_f32_e32 v132, v130
	v_rcp_f32_e32 v133, v100
	v_pk_mul_f32 v[70:71], v[118:119], v[70:71]
	v_add_f32_e32 v112, v116, v112
	v_pk_mul_f32 v[118:119], v[70:71], v[70:71]
	v_pk_mul_f32 v[100:101], v[132:133], v[128:129]
	v_lshlrev_b32_e32 v128, 16, v241
	v_and_b32_e32 v129, 0xffff0000, v241
	v_mul_f32_e32 v130, 0xbfb8aa3b, v128
	v_mul_f32_e32 v102, 0xbfb8aa3b, v129
	v_exp_f32_e32 v130, v130
	v_exp_f32_e32 v102, v102
	v_lshlrev_b32_e32 v132, 16, v238
	v_and_b32_e32 v133, 0xffff0000, v238
	v_add_f32_e32 v130, 1.0, v130
	v_add_f32_e32 v102, 1.0, v102
	v_rcp_f32_e32 v130, v130
	v_rcp_f32_e32 v131, v102
	v_add_f32_e32 v112, v117, v112
	v_pk_mul_f32 v[72:73], v[120:121], v[72:73]
	v_add_f32_e32 v112, v118, v112
	v_pk_mul_f32 v[102:103], v[130:131], v[128:129]
	ds_read2_b64 v[128:131], v136 offset0:12 offset1:14
	v_pk_mul_f32 v[120:121], v[72:73], v[72:73]
	v_add_f32_e32 v112, v119, v112
	v_pk_mul_f32 v[74:75], v[122:123], v[74:75]
	v_add_f32_e32 v112, v120, v112
	s_waitcnt lgkmcnt(0)
	v_lshlrev_b32_e32 v104, 16, v128
	v_and_b32_e32 v105, 0xffff0000, v128
	v_mul_f32_e32 v128, 0xbfb8aa3b, v132
	v_pk_fma_f32 v[40:41], v[162:163], v[104:105], v[40:41] op_sel_hi:[0,1,1]
	v_mul_f32_e32 v104, 0xbfb8aa3b, v133
	v_exp_f32_e32 v128, v128
	v_exp_f32_e32 v104, v104
	v_lshlrev_b32_e32 v106, 16, v129
	v_and_b32_e32 v107, 0xffff0000, v129
	v_add_f32_e32 v128, 1.0, v128
	v_add_f32_e32 v104, 1.0, v104
	v_rcp_f32_e32 v134, v128
	v_rcp_f32_e32 v135, v104
	v_lshlrev_b32_e32 v128, 16, v239
	v_and_b32_e32 v129, 0xffff0000, v239
	v_pk_fma_f32 v[42:43], v[162:163], v[106:107], v[42:43] op_sel_hi:[0,1,1]
	v_pk_mul_f32 v[104:105], v[134:135], v[132:133]
	v_mul_f32_e32 v132, 0xbfb8aa3b, v128
	v_mul_f32_e32 v106, 0xbfb8aa3b, v129
	v_exp_f32_e32 v132, v132
	v_exp_f32_e32 v106, v106
	v_lshlrev_b32_e32 v108, 16, v130
	v_and_b32_e32 v109, 0xffff0000, v130
	v_add_f32_e32 v132, 1.0, v132
	v_add_f32_e32 v106, 1.0, v106
	v_rcp_f32_e32 v132, v132
	v_rcp_f32_e32 v133, v106
	v_pk_fma_f32 v[44:45], v[162:163], v[108:109], v[44:45] op_sel_hi:[0,1,1]
	v_pk_mul_f32 v[122:123], v[74:75], v[74:75]
	v_add_f32_e32 v112, v121, v112
	v_pk_mul_f32 v[106:107], v[132:133], v[128:129]
	v_lshlrev_b32_e32 v128, 16, v236
	v_and_b32_e32 v129, 0xffff0000, v236
	v_mul_f32_e32 v130, 0xbfb8aa3b, v128
	v_mul_f32_e32 v108, 0xbfb8aa3b, v129
	v_exp_f32_e32 v130, v130
	v_exp_f32_e32 v108, v108
	v_pk_mul_f32 v[76:77], v[124:125], v[76:77]
	v_add_f32_e32 v112, v122, v112
	v_pk_mul_f32 v[124:125], v[76:77], v[76:77]
	v_add_f32_e32 v130, 1.0, v130
	v_add_f32_e32 v108, 1.0, v108
	v_add_f32_e32 v112, v123, v112
	v_pk_mul_f32 v[78:79], v[126:127], v[78:79]
	v_rcp_f32_e32 v132, v130
	v_rcp_f32_e32 v133, v108
	v_add_f32_e32 v112, v124, v112
	v_pk_mul_f32 v[126:127], v[78:79], v[78:79]
	v_add_f32_e32 v112, v125, v112
	v_pk_mul_f32 v[96:97], v[96:97], v[32:33]
	v_add_f32_e32 v112, v126, v112
	v_pk_mul_f32 v[32:33], v[96:97], v[96:97]
	v_add_f32_e32 v112, v127, v112
	v_pk_mul_f32 v[98:99], v[98:99], v[34:35]
	v_pk_mul_f32 v[108:109], v[132:133], v[128:129]
	v_lshlrev_b32_e32 v110, 16, v131
	v_and_b32_e32 v111, 0xffff0000, v131
	v_lshlrev_b32_e32 v128, 16, v237
	v_and_b32_e32 v129, 0xffff0000, v237
	v_add_f32_e32 v32, v32, v112
	v_pk_mul_f32 v[34:35], v[98:99], v[98:99]
	v_mul_f32_e32 v130, 0xbfb8aa3b, v128
	v_pk_fma_f32 v[46:47], v[162:163], v[110:111], v[46:47] op_sel_hi:[0,1,1]
	v_mul_f32_e32 v110, 0xbfb8aa3b, v129
	v_add_f32_e32 v32, v33, v32
	v_pk_mul_f32 v[100:101], v[100:101], v[36:37]
	v_exp_f32_e32 v130, v130
	v_exp_f32_e32 v110, v110
	v_add_f32_e32 v32, v34, v32
	v_pk_mul_f32 v[36:37], v[100:101], v[100:101]
	v_add_f32_e32 v32, v35, v32
	v_pk_mul_f32 v[102:103], v[102:103], v[38:39]
	v_add_f32_e32 v32, v36, v32
	v_pk_mul_f32 v[38:39], v[102:103], v[102:103]
	v_add_f32_e32 v32, v37, v32
	v_pk_mul_f32 v[104:105], v[104:105], v[40:41]
	v_add_f32_e32 v130, 1.0, v130
	v_add_f32_e32 v110, 1.0, v110
	v_add_f32_e32 v32, v38, v32
	v_pk_mul_f32 v[40:41], v[104:105], v[104:105]
	v_rcp_f32_e32 v130, v130
	v_rcp_f32_e32 v131, v110
	v_add_f32_e32 v32, v39, v32
	v_pk_mul_f32 v[106:107], v[106:107], v[42:43]
	v_add_f32_e32 v32, v40, v32
	v_pk_mul_f32 v[42:43], v[106:107], v[106:107]
	v_add_f32_e32 v32, v41, v32
	v_pk_mul_f32 v[108:109], v[108:109], v[44:45]
	v_add_f32_e32 v32, v42, v32
	v_pk_mul_f32 v[44:45], v[108:109], v[108:109]
	v_pk_mul_f32 v[110:111], v[130:131], v[128:129]
	v_add_f32_e32 v32, v43, v32
	v_pk_mul_f32 v[110:111], v[110:111], v[46:47]
	v_add_f32_e32 v32, v44, v32
	v_pk_mul_f32 v[46:47], v[110:111], v[110:111]
	v_add_f32_e32 v32, v45, v32
	v_add_f32_e32 v32, v46, v32
	v_xor_b32_e32 v113, 32, v184
	v_add_u32_e32 v114, 64, v139
	v_add_f32_e32 v112, v47, v32
	v_add_u32_e32 v32, 0x10400, v136
	v_cmp_lt_i32_e32 vcc, v113, v114
	ds_read2_b64 v[44:47], v32 offset1:2
	ds_read2_b64 v[40:43], v32 offset0:4 offset1:6
	ds_read2_b64 v[36:39], v32 offset0:8 offset1:10
	ds_read2_b64 v[32:35], v32 offset0:12 offset1:14
	v_cndmask_b32_e32 v113, v184, v113, vcc
	v_lshlrev_b32_e32 v115, 2, v113
	ds_bpermute_b32 v114, v115, v112
	v_add_u32_e32 v113, s6, v188
	s_and_saveexec_b64 s[2:3], s[42:43]
	s_cbranch_execz .LBB0_1847
	s_waitcnt lgkmcnt(0)
	v_add_f32_e32 v112, v112, v114
	ds_write_b32 v113, v112
.LBB0_1847:
	s_or_b64 exec, exec, s[2:3]
	s_waitcnt lgkmcnt(0)
	v_div_scale_f32 v114, s[2:3], v163, v163, v189
	v_rcp_f32_e32 v116, v114
	v_mul_f32_e32 v112, 0x3fb8aa3b, v143
	v_exp_f32_e32 v112, v112
	v_fma_f32 v117, -v114, v116, 1.0
	v_fmac_f32_e32 v116, v117, v116
	v_div_scale_f32 v117, vcc, v189, v163, v189
	v_mul_f32_e32 v118, v117, v116
	v_fma_f32 v119, -v114, v118, v117
	v_fmac_f32_e32 v118, v119, v116
	v_fma_f32 v114, -v114, v118, v117
	v_div_fmas_f32 v114, v114, v116, v118
	v_lshlrev_b32_e32 v116, 16, v234
	v_and_b32_e32 v117, 0xffff0000, v234
	v_mul_f32_e32 v118, 0xbfb8aa3b, v116
	v_mul_f32_e32 v119, 0xbfb8aa3b, v117
	v_exp_f32_e32 v118, v118
	v_exp_f32_e32 v119, v119
	v_pk_fma_f32 v[16:17], v[112:113], v[80:81], v[16:17] op_sel_hi:[0,1,1]
	v_div_fixup_f32 v114, v114, v163, v189
	v_add_f32_e32 v80, 1.0, v118
	v_add_f32_e32 v81, 1.0, v119
	v_rcp_f32_e32 v80, v80
	v_rcp_f32_e32 v81, v81
	v_lshlrev_b32_e32 v118, 16, v44
	v_and_b32_e32 v119, 0xffff0000, v44
	v_pk_fma_f32 v[16:17], v[114:115], v[118:119], v[16:17] op_sel_hi:[0,1,1]
	v_pk_mul_f32 v[80:81], v[80:81], v[116:117]
	v_lshlrev_b32_e32 v116, 16, v235
	v_and_b32_e32 v117, 0xffff0000, v235
	v_mul_f32_e32 v44, 0xbfb8aa3b, v116
	v_exp_f32_e32 v44, v44
	v_mul_f32_e32 v118, 0xbfb8aa3b, v117
	v_exp_f32_e32 v118, v118
	v_pk_fma_f32 v[18:19], v[112:113], v[82:83], v[18:19] op_sel_hi:[0,1,1]
	v_add_f32_e32 v44, 1.0, v44
	v_rcp_f32_e32 v82, v44
	v_add_f32_e32 v44, 1.0, v118
	v_rcp_f32_e32 v83, v44
	v_lshlrev_b32_e32 v44, 16, v45
	v_and_b32_e32 v45, 0xffff0000, v45
	v_pk_fma_f32 v[18:19], v[114:115], v[44:45], v[18:19] op_sel_hi:[0,1,1]
	v_pk_mul_f32 v[44:45], v[82:83], v[116:117]
	v_lshlrev_b32_e32 v82, 16, v232
	v_and_b32_e32 v83, 0xffff0000, v232
	v_mul_f32_e32 v116, 0xbfb8aa3b, v82
	v_mul_f32_e32 v117, 0xbfb8aa3b, v83
	v_exp_f32_e32 v116, v116
	v_exp_f32_e32 v117, v117
	v_pk_fma_f32 v[20:21], v[112:113], v[84:85], v[20:21] op_sel_hi:[0,1,1]
	v_pk_fma_f32 v[22:23], v[112:113], v[86:87], v[22:23] op_sel_hi:[0,1,1]
	v_add_f32_e32 v84, 1.0, v116
	v_add_f32_e32 v85, 1.0, v117
	v_rcp_f32_e32 v84, v84
	v_rcp_f32_e32 v85, v85
	v_lshlrev_b32_e32 v116, 16, v46
	v_and_b32_e32 v117, 0xffff0000, v46
	v_pk_fma_f32 v[20:21], v[114:115], v[116:117], v[20:21] op_sel_hi:[0,1,1]
	v_pk_mul_f32 v[82:83], v[84:85], v[82:83]
	v_lshlrev_b32_e32 v84, 16, v233
	v_and_b32_e32 v85, 0xffff0000, v233
	v_mul_f32_e32 v46, 0xbfb8aa3b, v84
	v_exp_f32_e32 v46, v46
	v_mul_f32_e32 v116, 0xbfb8aa3b, v85
	v_exp_f32_e32 v116, v116
	v_pk_fma_f32 v[24:25], v[112:113], v[88:89], v[24:25] op_sel_hi:[0,1,1]
	v_add_f32_e32 v46, 1.0, v46
	v_rcp_f32_e32 v86, v46
	v_add_f32_e32 v46, 1.0, v116
	v_rcp_f32_e32 v87, v46
	v_lshlrev_b32_e32 v46, 16, v47
	v_and_b32_e32 v47, 0xffff0000, v47
	v_pk_fma_f32 v[22:23], v[114:115], v[46:47], v[22:23] op_sel_hi:[0,1,1]
	v_pk_mul_f32 v[46:47], v[86:87], v[84:85]
	v_lshlrev_b32_e32 v84, 16, v230
	v_and_b32_e32 v85, 0xffff0000, v230
	v_mul_f32_e32 v86, 0xbfb8aa3b, v84
	v_mul_f32_e32 v87, 0xbfb8aa3b, v85
	v_exp_f32_e32 v86, v86
	v_exp_f32_e32 v87, v87
	v_lshlrev_b32_e32 v88, 16, v40
	v_and_b32_e32 v89, 0xffff0000, v40
	v_add_f32_e32 v86, 1.0, v86
	v_add_f32_e32 v87, 1.0, v87
	v_rcp_f32_e32 v86, v86
	v_rcp_f32_e32 v87, v87
	v_pk_fma_f32 v[24:25], v[114:115], v[88:89], v[24:25] op_sel_hi:[0,1,1]
	v_pk_fma_f32 v[26:27], v[112:113], v[90:91], v[26:27] op_sel_hi:[0,1,1]
	v_pk_fma_f32 v[28:29], v[112:113], v[92:93], v[28:29] op_sel_hi:[0,1,1]
	v_pk_mul_f32 v[84:85], v[86:87], v[84:85]
	v_lshlrev_b32_e32 v86, 16, v231
	v_and_b32_e32 v87, 0xffff0000, v231
	v_mul_f32_e32 v40, 0xbfb8aa3b, v86
	v_exp_f32_e32 v40, v40
	v_mul_f32_e32 v88, 0xbfb8aa3b, v87
	v_exp_f32_e32 v89, v88
	v_lshlrev_b32_e32 v90, 16, v42
	v_add_f32_e32 v40, 1.0, v40
	v_rcp_f32_e32 v88, v40
	v_add_f32_e32 v40, 1.0, v89
	v_rcp_f32_e32 v89, v40
	v_lshlrev_b32_e32 v40, 16, v41
	v_and_b32_e32 v41, 0xffff0000, v41
	v_pk_fma_f32 v[26:27], v[114:115], v[40:41], v[26:27] op_sel_hi:[0,1,1]
	v_pk_mul_f32 v[40:41], v[88:89], v[86:87]
	v_lshlrev_b32_e32 v86, 16, v228
	v_and_b32_e32 v87, 0xffff0000, v228
	v_mul_f32_e32 v88, 0xbfb8aa3b, v86
	v_mul_f32_e32 v89, 0xbfb8aa3b, v87
	v_exp_f32_e32 v88, v88
	v_exp_f32_e32 v89, v89
	v_and_b32_e32 v91, 0xffff0000, v42
	v_pk_fma_f32 v[28:29], v[114:115], v[90:91], v[28:29] op_sel_hi:[0,1,1]
	v_add_f32_e32 v88, 1.0, v88
	v_add_f32_e32 v89, 1.0, v89
	v_rcp_f32_e32 v88, v88
	v_rcp_f32_e32 v89, v89
	v_pk_fma_f32 v[30:31], v[112:113], v[94:95], v[30:31] op_sel_hi:[0,1,1]
	v_pk_fma_f32 v[0:1], v[112:113], v[48:49], v[0:1] op_sel_hi:[0,1,1]
	v_pk_fma_f32 v[2:3], v[112:113], v[50:51], v[2:3] op_sel_hi:[0,1,1]
	v_pk_mul_f32 v[86:87], v[88:89], v[86:87]
	v_lshlrev_b32_e32 v88, 16, v229
	v_and_b32_e32 v89, 0xffff0000, v229
	v_mul_f32_e32 v42, 0xbfb8aa3b, v88
	v_exp_f32_e32 v42, v42
	v_mul_f32_e32 v90, 0xbfb8aa3b, v89
	v_exp_f32_e32 v91, v90
	v_pk_fma_f32 v[4:5], v[112:113], v[52:53], v[4:5] op_sel_hi:[0,1,1]
	v_add_f32_e32 v42, 1.0, v42
	v_rcp_f32_e32 v90, v42
	v_add_f32_e32 v42, 1.0, v91
	v_rcp_f32_e32 v91, v42
	v_lshlrev_b32_e32 v42, 16, v43
	v_and_b32_e32 v43, 0xffff0000, v43
	v_pk_fma_f32 v[30:31], v[114:115], v[42:43], v[30:31] op_sel_hi:[0,1,1]
	v_pk_mul_f32 v[42:43], v[90:91], v[88:89]
	v_lshlrev_b32_e32 v88, 16, v226
	v_and_b32_e32 v89, 0xffff0000, v226
	v_mul_f32_e32 v90, 0xbfb8aa3b, v88
	v_mul_f32_e32 v91, 0xbfb8aa3b, v89
	v_exp_f32_e32 v90, v90
	v_exp_f32_e32 v91, v91
	v_pk_fma_f32 v[6:7], v[112:113], v[54:55], v[6:7] op_sel_hi:[0,1,1]
	v_pk_fma_f32 v[8:9], v[112:113], v[56:57], v[8:9] op_sel_hi:[0,1,1]
	v_add_f32_e32 v48, 1.0, v90
	v_add_f32_e32 v49, 1.0, v91
	v_rcp_f32_e32 v48, v48
	v_rcp_f32_e32 v49, v49
	v_lshlrev_b32_e32 v90, 16, v36
	v_and_b32_e32 v91, 0xffff0000, v36
	v_pk_fma_f32 v[0:1], v[114:115], v[90:91], v[0:1] op_sel_hi:[0,1,1]
	v_pk_mul_f32 v[48:49], v[48:49], v[88:89]
	v_lshlrev_b32_e32 v88, 16, v227
	v_and_b32_e32 v89, 0xffff0000, v227
	v_mul_f32_e32 v36, 0xbfb8aa3b, v88
	v_exp_f32_e32 v36, v36
	v_mul_f32_e32 v90, 0xbfb8aa3b, v89
	v_exp_f32_e32 v90, v90
	v_lshlrev_b32_e32 v56, 16, v32
	v_add_f32_e32 v36, 1.0, v36
	v_rcp_f32_e32 v50, v36
	v_add_f32_e32 v36, 1.0, v90
	v_rcp_f32_e32 v51, v36
	v_lshlrev_b32_e32 v36, 16, v37
	v_and_b32_e32 v37, 0xffff0000, v37
	v_pk_fma_f32 v[2:3], v[114:115], v[36:37], v[2:3] op_sel_hi:[0,1,1]
	v_pk_mul_f32 v[36:37], v[50:51], v[88:89]
	v_lshlrev_b32_e32 v50, 16, v224
	v_and_b32_e32 v51, 0xffff0000, v224
	v_mul_f32_e32 v88, 0xbfb8aa3b, v50
	v_mul_f32_e32 v89, 0xbfb8aa3b, v51
	v_exp_f32_e32 v88, v88
	v_exp_f32_e32 v89, v89
	v_and_b32_e32 v57, 0xffff0000, v32
	v_pk_fma_f32 v[8:9], v[114:115], v[56:57], v[8:9] op_sel_hi:[0,1,1]
	v_add_f32_e32 v52, 1.0, v88
	v_add_f32_e32 v53, 1.0, v89
	v_rcp_f32_e32 v52, v52
	v_rcp_f32_e32 v53, v53
	v_lshlrev_b32_e32 v88, 16, v38
	v_and_b32_e32 v89, 0xffff0000, v38
	v_pk_fma_f32 v[4:5], v[114:115], v[88:89], v[4:5] op_sel_hi:[0,1,1]
	v_pk_mul_f32 v[50:51], v[52:53], v[50:51]
	v_lshlrev_b32_e32 v52, 16, v225
	v_and_b32_e32 v53, 0xffff0000, v225
	v_mul_f32_e32 v38, 0xbfb8aa3b, v52
	v_exp_f32_e32 v38, v38
	v_mul_f32_e32 v88, 0xbfb8aa3b, v53
	v_exp_f32_e32 v88, v88
	v_pk_mul_f32 v[80:81], v[80:81], v[16:17]
	v_add_f32_e32 v38, 1.0, v38
	v_rcp_f32_e32 v54, v38
	v_add_f32_e32 v38, 1.0, v88
	v_rcp_f32_e32 v55, v38
	v_lshlrev_b32_e32 v38, 16, v39
	v_and_b32_e32 v39, 0xffff0000, v39
	v_pk_fma_f32 v[6:7], v[114:115], v[38:39], v[6:7] op_sel_hi:[0,1,1]
	v_pk_mul_f32 v[38:39], v[54:55], v[52:53]
	v_lshlrev_b32_e32 v52, 16, v222
	v_and_b32_e32 v53, 0xffff0000, v222
	v_mul_f32_e32 v54, 0xbfb8aa3b, v52
	v_mul_f32_e32 v55, 0xbfb8aa3b, v53
	v_exp_f32_e32 v54, v54
	v_exp_f32_e32 v55, v55
	v_pk_mul_f32 v[16:17], v[80:81], v[80:81]
	v_pk_mul_f32 v[44:45], v[44:45], v[18:19]
	v_add_f32_e32 v54, 1.0, v54
	v_add_f32_e32 v55, 1.0, v55
	v_rcp_f32_e32 v54, v54
	v_rcp_f32_e32 v55, v55
	v_pk_mul_f32 v[18:19], v[44:45], v[44:45]
	v_add_f32_e32 v16, v16, v17
	v_pk_mul_f32 v[82:83], v[82:83], v[20:21]
	v_pk_mul_f32 v[52:53], v[54:55], v[52:53]
	v_lshlrev_b32_e32 v54, 16, v223
	v_and_b32_e32 v55, 0xffff0000, v223
	v_mul_f32_e32 v32, 0xbfb8aa3b, v54
	v_exp_f32_e32 v32, v32
	v_mul_f32_e32 v56, 0xbfb8aa3b, v55
	v_exp_f32_e32 v57, v56
	v_add_f32_e32 v16, v18, v16
	v_add_f32_e32 v32, 1.0, v32
	v_rcp_f32_e32 v56, v32
	v_add_f32_e32 v32, 1.0, v57
	v_rcp_f32_e32 v57, v32
	v_pk_mul_f32 v[20:21], v[82:83], v[82:83]
	v_pk_fma_f32 v[10:11], v[112:113], v[58:59], v[10:11] op_sel_hi:[0,1,1]
	v_lshlrev_b32_e32 v32, 16, v33
	v_and_b32_e32 v33, 0xffff0000, v33
	v_add_f32_e32 v16, v19, v16
	v_pk_mul_f32 v[46:47], v[46:47], v[22:23]
	v_pk_fma_f32 v[10:11], v[114:115], v[32:33], v[10:11] op_sel_hi:[0,1,1]
	v_pk_mul_f32 v[32:33], v[56:57], v[54:55]
	v_lshlrev_b32_e32 v54, 16, v220
	v_and_b32_e32 v55, 0xffff0000, v220
	v_add_f32_e32 v16, v20, v16
	v_pk_mul_f32 v[22:23], v[46:47], v[46:47]
	v_mul_f32_e32 v56, 0xbfb8aa3b, v54
	v_mul_f32_e32 v57, 0xbfb8aa3b, v55
	v_add_f32_e32 v16, v21, v16
	v_pk_mul_f32 v[84:85], v[84:85], v[24:25]
	v_exp_f32_e32 v56, v56
	v_exp_f32_e32 v57, v57
	v_add_f32_e32 v16, v22, v16
	v_pk_mul_f32 v[24:25], v[84:85], v[84:85]
	v_add_f32_e32 v16, v23, v16
	v_pk_mul_f32 v[40:41], v[40:41], v[26:27]
	v_add_f32_e32 v16, v24, v16
	v_pk_mul_f32 v[26:27], v[40:41], v[40:41]
	v_add_f32_e32 v16, v25, v16
	v_pk_mul_f32 v[86:87], v[86:87], v[28:29]
	v_add_f32_e32 v56, 1.0, v56
	v_add_f32_e32 v57, 1.0, v57
	v_add_f32_e32 v16, v26, v16
	v_pk_mul_f32 v[28:29], v[86:87], v[86:87]
	v_rcp_f32_e32 v56, v56
	v_rcp_f32_e32 v57, v57
	v_add_f32_e32 v16, v27, v16
	v_pk_mul_f32 v[42:43], v[42:43], v[30:31]
	v_add_f32_e32 v16, v28, v16
	v_pk_mul_f32 v[30:31], v[42:43], v[42:43]
	v_add_f32_e32 v16, v29, v16
	v_pk_mul_f32 v[48:49], v[48:49], v[0:1]
	v_add_f32_e32 v16, v30, v16
	v_pk_mul_f32 v[0:1], v[48:49], v[48:49]
	v_pk_mul_f32 v[54:55], v[56:57], v[54:55]
	v_lshlrev_b32_e32 v56, 16, v221
	v_add_f32_e32 v16, v31, v16
	v_pk_mul_f32 v[36:37], v[36:37], v[2:3]
	v_pk_fma_f32 v[12:13], v[112:113], v[60:61], v[12:13] op_sel_hi:[0,1,1]
	v_lshlrev_b32_e32 v58, 16, v34
	v_and_b32_e32 v59, 0xffff0000, v34
	v_and_b32_e32 v57, 0xffff0000, v221
	v_mul_f32_e32 v34, 0xbfb8aa3b, v56
	v_add_f32_e32 v0, v0, v16
	v_pk_mul_f32 v[2:3], v[36:37], v[36:37]
	v_pk_fma_f32 v[12:13], v[114:115], v[58:59], v[12:13] op_sel_hi:[0,1,1]
	v_exp_f32_e32 v34, v34
	v_mul_f32_e32 v58, 0xbfb8aa3b, v57
	v_add_f32_e32 v0, v1, v0
	v_pk_mul_f32 v[50:51], v[50:51], v[4:5]
	v_exp_f32_e32 v59, v58
	v_add_f32_e32 v0, v2, v0
	v_pk_mul_f32 v[4:5], v[50:51], v[50:51]
	v_add_f32_e32 v0, v3, v0
	v_pk_mul_f32 v[38:39], v[38:39], v[6:7]
	v_add_f32_e32 v0, v4, v0
	v_pk_mul_f32 v[6:7], v[38:39], v[38:39]
	v_add_f32_e32 v34, 1.0, v34
	v_add_f32_e32 v0, v5, v0
	v_pk_mul_f32 v[52:53], v[52:53], v[8:9]
	v_rcp_f32_e32 v58, v34
	v_add_f32_e32 v34, 1.0, v59
	v_add_f32_e32 v0, v6, v0
	v_pk_mul_f32 v[8:9], v[52:53], v[52:53]
	v_rcp_f32_e32 v59, v34
	v_add_f32_e32 v0, v7, v0
	v_pk_mul_f32 v[32:33], v[32:33], v[10:11]
	v_add_f32_e32 v0, v8, v0
	v_pk_mul_f32 v[10:11], v[32:33], v[32:33]
	v_add_f32_e32 v0, v9, v0
	v_pk_mul_f32 v[54:55], v[54:55], v[12:13]
	v_pk_fma_f32 v[14:15], v[112:113], v[62:63], v[14:15] op_sel_hi:[0,1,1]
	v_lshlrev_b32_e32 v34, 16, v35
	v_and_b32_e32 v35, 0xffff0000, v35
	v_add_f32_e32 v0, v10, v0
	v_pk_mul_f32 v[12:13], v[54:55], v[54:55]
	v_pk_fma_f32 v[14:15], v[114:115], v[34:35], v[14:15] op_sel_hi:[0,1,1]
	v_pk_mul_f32 v[34:35], v[58:59], v[56:57]
	v_add_f32_e32 v0, v11, v0
	v_pk_mul_f32 v[34:35], v[34:35], v[14:15]
	v_add_f32_e32 v0, v12, v0
	v_pk_mul_f32 v[14:15], v[34:35], v[34:35]
	v_add_f32_e32 v0, v13, v0
	v_add_f32_e32 v0, v14, v0
	v_add_f32_e32 v0, v15, v0
	ds_bpermute_b32 v1, v115, v0
	s_and_saveexec_b64 s[2:3], s[42:43]
	s_cbranch_execz .LBB0_1694
	s_waitcnt lgkmcnt(0)
	v_add_f32_e32 v0, v0, v1
	ds_write_b32 v113, v0 offset:128
	s_branch .LBB0_1694
